# BM selected-attention: after a group's section, leave the block directly when no later group selects it (instead of three more test+skip branches)
# baseline (speedup 1.0000x reference)
.Lbm2_nostag:
.Lbm2_blkA:
	s_lshl_b32 s12, s15, 12
	s_add_u32 s30, s46, s12
	s_addc_u32 s31, s47, 0
	global_load_dwordx4 v[20:23], v79, s[30:31]
	global_load_dwordx4 v[24:27], v79, s[30:31] offset:1024
	global_load_dwordx4 v[28:31], v79, s[30:31] offset:2048
	global_load_dwordx4 v[32:35], v79, s[30:31] offset:3072
	s_lshl_b32 s12, s15, 12
	s_add_u32 s30, s62, s12
	s_addc_u32 s31, s63, 0
	global_load_dwordx4 v[52:55], v79, s[30:31]
	global_load_dwordx4 v[56:59], v79, s[30:31] offset:1024
	global_load_dwordx4 v[60:63], v79, s[30:31] offset:2048
	global_load_dwordx4 v[64:67], v79, s[30:31] offset:3072
	s_add_i32 s14, s35, 2
	s_add_i32 s13, s25, -1
	s_min_i32 s14, s14, s13
	s_lshl_b32 s13, s14, 2
	s_add_i32 s13, s13, s96
	v_mov_b32_e32 v76, s13
	ds_read_b32 v76, v76 offset:16384
	s_cmp_ge_i32 s54, s21
	s_cselect_b32 s14, 1, 0
	s_bfe_u32 s29, s48, 0x40000
	s_cmp_eq_u32 s29, 0
	s_cbranch_scc1 .Lbm2_Ag0_skip
	s_waitcnt vmcnt(12)
	v_mfma_f32_16x16x32_fp8_fp8 v[84:87], v[2:3], v[164:165], 0
	v_mfma_f32_16x16x32_fp8_fp8 v[88:91], v[6:7], v[164:165], 0
	v_mfma_f32_16x16x32_fp8_fp8 v[92:95], v[12:13], v[164:165], 0
	v_mfma_f32_16x16x32_fp8_fp8 v[96:99], v[16:17], v[164:165], 0
	v_mfma_f32_16x16x32_fp8_fp8 v[84:87], v[4:5], v[166:167], v[84:87]
	v_mfma_f32_16x16x32_fp8_fp8 v[88:91], v[8:9], v[166:167], v[88:91]
	v_mfma_f32_16x16x32_fp8_fp8 v[92:95], v[14:15], v[166:167], v[92:95]
	v_mfma_f32_16x16x32_fp8_fp8 v[96:99], v[18:19], v[166:167], v[96:99]
	v_and_b32_e32 v199, s29, v244
	s_cmp_eq_u32 s14, 1
	v_cmp_ne_u32_e32 vcc, 0, v199
	s_cbranch_scc1 .Lbm2_Ag0_near
	v_add_f32_e32 v200, v81, v190
	v_cndmask_b32_e32 v200, v77, v200, vcc
	s_cmp_eq_u32 s35, 0
	s_cbranch_scc1 .Lbm2_Ag0_first
	v_pk_fma_f32 v[84:85], v[84:85], s[16:17], v[200:201] op_sel_hi:[1,1,0]
	v_pk_fma_f32 v[86:87], v[86:87], s[16:17], v[200:201] op_sel_hi:[1,1,0]
	v_pk_fma_f32 v[88:89], v[88:89], s[16:17], v[200:201] op_sel_hi:[1,1,0]
	v_pk_fma_f32 v[90:91], v[90:91], s[16:17], v[200:201] op_sel_hi:[1,1,0]
	v_exp_f32_e32 v84, v84
	v_exp_f32_e32 v85, v85
	v_exp_f32_e32 v86, v86
	v_exp_f32_e32 v87, v87
	v_pk_fma_f32 v[92:93], v[92:93], s[16:17], v[200:201] op_sel_hi:[1,1,0]
	v_pk_fma_f32 v[94:95], v[94:95], s[16:17], v[200:201] op_sel_hi:[1,1,0]
	v_exp_f32_e32 v88, v88
	v_exp_f32_e32 v89, v89
	v_exp_f32_e32 v90, v90
	v_exp_f32_e32 v91, v91
	v_pk_fma_f32 v[96:97], v[96:97], s[16:17], v[200:201] op_sel_hi:[1,1,0]
	v_pk_fma_f32 v[98:99], v[98:99], s[16:17], v[200:201] op_sel_hi:[1,1,0]
	v_exp_f32_e32 v92, v92
	v_exp_f32_e32 v93, v93
	v_exp_f32_e32 v94, v94
	v_exp_f32_e32 v95, v95
	s_nop 0
	v_exp_f32_e32 v96, v96
	v_exp_f32_e32 v97, v97
	v_exp_f32_e32 v98, v98
	v_exp_f32_e32 v99, v99
	v_pk_add_f32 v[248:249], v[84:85], v[86:87]
	v_pk_add_f32 v[82:83], v[88:89], v[90:91]
	v_pk_add_f32 v[172:173], v[92:93], v[94:95]
	v_pk_add_f32 v[202:203], v[96:97], v[98:99]
	v_cvt_pk_fp8_f32 v84, v84, v85
	v_cvt_pk_fp8_f32 v85, v88, v89
	v_pk_add_f32 v[248:249], v[248:249], v[82:83]
	v_pk_add_f32 v[172:173], v[172:173], v[202:203]
	v_cvt_pk_fp8_f32 v84, v86, v87 op_sel:[0,0,1]
	v_cvt_pk_fp8_f32 v85, v90, v91 op_sel:[0,0,1]
	v_pk_add_f32 v[248:249], v[248:249], v[172:173]
	v_cvt_pk_fp8_f32 v86, v92, v93
	v_cvt_pk_fp8_f32 v87, v96, v97
	v_add_f32_e32 v248, v248, v249
	v_cvt_pk_fp8_f32 v86, v94, v95 op_sel:[0,0,1]
	v_cvt_pk_fp8_f32 v87, v98, v99 op_sel:[0,0,1]
	v_cmp_lt_f32_e32 vcc, 0x43800000, v248
	s_cbranch_vccnz .Lbm2_Ag0_redo
	v_add_f32_e32 v194, v194, v248
	s_waitcnt vmcnt(8)
	v_mfma_f32_16x16x32_fp8_fp8 v[100:103], v[36:37], v[84:85], v[100:103]
	v_mfma_f32_16x16x32_fp8_fp8 v[104:107], v[38:39], v[84:85], v[104:107]
	v_mfma_f32_16x16x32_fp8_fp8 v[108:111], v[40:41], v[84:85], v[108:111]
	v_mfma_f32_16x16x32_fp8_fp8 v[112:115], v[42:43], v[84:85], v[112:115]
	v_mfma_f32_16x16x32_fp8_fp8 v[100:103], v[44:45], v[86:87], v[100:103]
	v_mfma_f32_16x16x32_fp8_fp8 v[104:107], v[46:47], v[86:87], v[104:107]
	v_mfma_f32_16x16x32_fp8_fp8 v[108:111], v[48:49], v[86:87], v[108:111]
	v_mfma_f32_16x16x32_fp8_fp8 v[112:115], v[50:51], v[86:87], v[112:115]
	s_lshr_b32 s29, s48, 4
	s_cmp_eq_u32 s29, 0
	s_cbranch_scc1 .Lbm2_Ag3_skip
	s_branch .Lbm2_Ag0_skip

.Lbm2_Ag0_exp:
	v_exp_f32_e32 v84, v84
	v_exp_f32_e32 v85, v85
	v_exp_f32_e32 v86, v86
	v_exp_f32_e32 v87, v87
	v_exp_f32_e32 v88, v88
	v_exp_f32_e32 v89, v89
	v_exp_f32_e32 v90, v90
	v_exp_f32_e32 v91, v91
	v_exp_f32_e32 v92, v92
	v_exp_f32_e32 v93, v93
	v_exp_f32_e32 v94, v94
	v_exp_f32_e32 v95, v95
	v_exp_f32_e32 v96, v96
	v_exp_f32_e32 v97, v97
	v_exp_f32_e32 v98, v98
	v_exp_f32_e32 v99, v99
	v_pk_add_f32 v[248:249], v[84:85], v[86:87]
	v_pk_add_f32 v[248:249], v[248:249], v[88:89]
	v_pk_add_f32 v[248:249], v[248:249], v[90:91]
	v_pk_add_f32 v[248:249], v[248:249], v[92:93]
	v_pk_add_f32 v[248:249], v[248:249], v[94:95]
	v_pk_add_f32 v[248:249], v[248:249], v[96:97]
	v_pk_add_f32 v[248:249], v[248:249], v[98:99]
	v_cvt_pk_fp8_f32 v84, v84, v85
	v_cvt_pk_fp8_f32 v85, v88, v89
	v_cvt_pk_fp8_f32 v84, v86, v87 op_sel:[0,0,1]
	v_cvt_pk_fp8_f32 v85, v90, v91 op_sel:[0,0,1]
	v_cvt_pk_fp8_f32 v86, v92, v93
	v_cvt_pk_fp8_f32 v87, v96, v97
	v_cvt_pk_fp8_f32 v86, v94, v95 op_sel:[0,0,1]
	v_cvt_pk_fp8_f32 v87, v98, v99 op_sel:[0,0,1]
	v_add_f32_e32 v248, v248, v249
	v_add_f32_e32 v194, v194, v248
	s_waitcnt vmcnt(8)
	v_mfma_f32_16x16x32_fp8_fp8 v[100:103], v[36:37], v[84:85], v[100:103]
	v_mfma_f32_16x16x32_fp8_fp8 v[104:107], v[38:39], v[84:85], v[104:107]
	v_mfma_f32_16x16x32_fp8_fp8 v[108:111], v[40:41], v[84:85], v[108:111]
	v_mfma_f32_16x16x32_fp8_fp8 v[112:115], v[42:43], v[84:85], v[112:115]
	v_mfma_f32_16x16x32_fp8_fp8 v[100:103], v[44:45], v[86:87], v[100:103]
	v_mfma_f32_16x16x32_fp8_fp8 v[104:107], v[46:47], v[86:87], v[104:107]
	v_mfma_f32_16x16x32_fp8_fp8 v[108:111], v[48:49], v[86:87], v[108:111]
	v_mfma_f32_16x16x32_fp8_fp8 v[112:115], v[50:51], v[86:87], v[112:115]
	s_lshr_b32 s29, s48, 4
	s_cmp_eq_u32 s29, 0
	s_cbranch_scc1 .Lbm2_Ag3_skip
	s_branch .Lbm2_Ag0_skip

.Lbm2_Ag0_skip:
	s_bfe_u32 s29, s48, 0x40004
	s_cmp_eq_u32 s29, 0
	s_cbranch_scc1 .Lbm2_Ag1_skip
	s_waitcnt vmcnt(12)
	v_mfma_f32_16x16x32_fp8_fp8 v[84:87], v[2:3], v[168:169], 0
	v_mfma_f32_16x16x32_fp8_fp8 v[88:91], v[6:7], v[168:169], 0
	v_mfma_f32_16x16x32_fp8_fp8 v[92:95], v[12:13], v[168:169], 0
	v_mfma_f32_16x16x32_fp8_fp8 v[96:99], v[16:17], v[168:169], 0
	v_mfma_f32_16x16x32_fp8_fp8 v[84:87], v[4:5], v[170:171], v[84:87]
	v_mfma_f32_16x16x32_fp8_fp8 v[88:91], v[8:9], v[170:171], v[88:91]
	v_mfma_f32_16x16x32_fp8_fp8 v[92:95], v[14:15], v[170:171], v[92:95]
	v_mfma_f32_16x16x32_fp8_fp8 v[96:99], v[18:19], v[170:171], v[96:99]
	v_and_b32_e32 v199, s29, v244
	s_cmp_eq_u32 s14, 1
	v_cmp_ne_u32_e32 vcc, 0, v199
	s_cbranch_scc1 .Lbm2_Ag1_near
	v_add_f32_e32 v200, v81, v191
	v_cndmask_b32_e32 v200, v77, v200, vcc
	s_cmp_eq_u32 s35, 0
	s_cbranch_scc1 .Lbm2_Ag1_first
	v_pk_fma_f32 v[84:85], v[84:85], s[16:17], v[200:201] op_sel_hi:[1,1,0]
	v_pk_fma_f32 v[86:87], v[86:87], s[16:17], v[200:201] op_sel_hi:[1,1,0]
	v_pk_fma_f32 v[88:89], v[88:89], s[16:17], v[200:201] op_sel_hi:[1,1,0]
	v_pk_fma_f32 v[90:91], v[90:91], s[16:17], v[200:201] op_sel_hi:[1,1,0]
	v_exp_f32_e32 v84, v84
	v_exp_f32_e32 v85, v85
	v_exp_f32_e32 v86, v86
	v_exp_f32_e32 v87, v87
	v_pk_fma_f32 v[92:93], v[92:93], s[16:17], v[200:201] op_sel_hi:[1,1,0]
	v_pk_fma_f32 v[94:95], v[94:95], s[16:17], v[200:201] op_sel_hi:[1,1,0]
	v_exp_f32_e32 v88, v88
	v_exp_f32_e32 v89, v89
	v_exp_f32_e32 v90, v90
	v_exp_f32_e32 v91, v91
	v_pk_fma_f32 v[96:97], v[96:97], s[16:17], v[200:201] op_sel_hi:[1,1,0]
	v_pk_fma_f32 v[98:99], v[98:99], s[16:17], v[200:201] op_sel_hi:[1,1,0]
	v_exp_f32_e32 v92, v92
	v_exp_f32_e32 v93, v93
	v_exp_f32_e32 v94, v94
	v_exp_f32_e32 v95, v95
	s_nop 0
	v_exp_f32_e32 v96, v96
	v_exp_f32_e32 v97, v97
	v_exp_f32_e32 v98, v98
	v_exp_f32_e32 v99, v99
	v_pk_add_f32 v[248:249], v[84:85], v[86:87]
	v_pk_add_f32 v[82:83], v[88:89], v[90:91]
	v_pk_add_f32 v[172:173], v[92:93], v[94:95]
	v_pk_add_f32 v[202:203], v[96:97], v[98:99]
	v_cvt_pk_fp8_f32 v84, v84, v85
	v_cvt_pk_fp8_f32 v85, v88, v89
	v_pk_add_f32 v[248:249], v[248:249], v[82:83]
	v_pk_add_f32 v[172:173], v[172:173], v[202:203]
	v_cvt_pk_fp8_f32 v84, v86, v87 op_sel:[0,0,1]
	v_cvt_pk_fp8_f32 v85, v90, v91 op_sel:[0,0,1]
	v_pk_add_f32 v[248:249], v[248:249], v[172:173]
	v_cvt_pk_fp8_f32 v86, v92, v93
	v_cvt_pk_fp8_f32 v87, v96, v97
	v_add_f32_e32 v248, v248, v249
	v_cvt_pk_fp8_f32 v86, v94, v95 op_sel:[0,0,1]
	v_cvt_pk_fp8_f32 v87, v98, v99 op_sel:[0,0,1]
	v_cmp_lt_f32_e32 vcc, 0x43800000, v248
	s_cbranch_vccnz .Lbm2_Ag1_redo
	v_add_f32_e32 v195, v195, v248
	s_waitcnt vmcnt(8)
	v_mfma_f32_16x16x32_fp8_fp8 v[116:119], v[36:37], v[84:85], v[116:119]
	v_mfma_f32_16x16x32_fp8_fp8 v[120:123], v[38:39], v[84:85], v[120:123]
	v_mfma_f32_16x16x32_fp8_fp8 v[124:127], v[40:41], v[84:85], v[124:127]
	v_mfma_f32_16x16x32_fp8_fp8 v[128:131], v[42:43], v[84:85], v[128:131]
	v_mfma_f32_16x16x32_fp8_fp8 v[116:119], v[44:45], v[86:87], v[116:119]
	v_mfma_f32_16x16x32_fp8_fp8 v[120:123], v[46:47], v[86:87], v[120:123]
	v_mfma_f32_16x16x32_fp8_fp8 v[124:127], v[48:49], v[86:87], v[124:127]
	v_mfma_f32_16x16x32_fp8_fp8 v[128:131], v[50:51], v[86:87], v[128:131]
	s_lshr_b32 s29, s48, 8
	s_cmp_eq_u32 s29, 0
	s_cbranch_scc1 .Lbm2_Ag3_skip
	s_branch .Lbm2_Ag1_skip

.Lbm2_Ag1_exp:
	v_exp_f32_e32 v84, v84
	v_exp_f32_e32 v85, v85
	v_exp_f32_e32 v86, v86
	v_exp_f32_e32 v87, v87
	v_exp_f32_e32 v88, v88
	v_exp_f32_e32 v89, v89
	v_exp_f32_e32 v90, v90
	v_exp_f32_e32 v91, v91
	v_exp_f32_e32 v92, v92
	v_exp_f32_e32 v93, v93
	v_exp_f32_e32 v94, v94
	v_exp_f32_e32 v95, v95
	v_exp_f32_e32 v96, v96
	v_exp_f32_e32 v97, v97
	v_exp_f32_e32 v98, v98
	v_exp_f32_e32 v99, v99
	v_pk_add_f32 v[248:249], v[84:85], v[86:87]
	v_pk_add_f32 v[248:249], v[248:249], v[88:89]
	v_pk_add_f32 v[248:249], v[248:249], v[90:91]
	v_pk_add_f32 v[248:249], v[248:249], v[92:93]
	v_pk_add_f32 v[248:249], v[248:249], v[94:95]
	v_pk_add_f32 v[248:249], v[248:249], v[96:97]
	v_pk_add_f32 v[248:249], v[248:249], v[98:99]
	v_cvt_pk_fp8_f32 v84, v84, v85
	v_cvt_pk_fp8_f32 v85, v88, v89
	v_cvt_pk_fp8_f32 v84, v86, v87 op_sel:[0,0,1]
	v_cvt_pk_fp8_f32 v85, v90, v91 op_sel:[0,0,1]
	v_cvt_pk_fp8_f32 v86, v92, v93
	v_cvt_pk_fp8_f32 v87, v96, v97
	v_cvt_pk_fp8_f32 v86, v94, v95 op_sel:[0,0,1]
	v_cvt_pk_fp8_f32 v87, v98, v99 op_sel:[0,0,1]
	v_add_f32_e32 v248, v248, v249
	v_add_f32_e32 v195, v195, v248
	s_waitcnt vmcnt(8)
	v_mfma_f32_16x16x32_fp8_fp8 v[116:119], v[36:37], v[84:85], v[116:119]
	v_mfma_f32_16x16x32_fp8_fp8 v[120:123], v[38:39], v[84:85], v[120:123]
	v_mfma_f32_16x16x32_fp8_fp8 v[124:127], v[40:41], v[84:85], v[124:127]
	v_mfma_f32_16x16x32_fp8_fp8 v[128:131], v[42:43], v[84:85], v[128:131]
	v_mfma_f32_16x16x32_fp8_fp8 v[116:119], v[44:45], v[86:87], v[116:119]
	v_mfma_f32_16x16x32_fp8_fp8 v[120:123], v[46:47], v[86:87], v[120:123]
	v_mfma_f32_16x16x32_fp8_fp8 v[124:127], v[48:49], v[86:87], v[124:127]
	v_mfma_f32_16x16x32_fp8_fp8 v[128:131], v[50:51], v[86:87], v[128:131]
	s_lshr_b32 s29, s48, 8
	s_cmp_eq_u32 s29, 0
	s_cbranch_scc1 .Lbm2_Ag3_skip
	s_branch .Lbm2_Ag1_skip

.Lbm2_Ag1_skip:
	s_bfe_u32 s29, s48, 0x40008
	s_cmp_eq_u32 s29, 0
	s_cbranch_scc1 .Lbm2_Ag2_skip
	s_waitcnt vmcnt(12)
	v_mfma_f32_16x16x32_fp8_fp8 v[84:87], v[2:3], v[182:183], 0
	v_mfma_f32_16x16x32_fp8_fp8 v[88:91], v[6:7], v[182:183], 0
	v_mfma_f32_16x16x32_fp8_fp8 v[92:95], v[12:13], v[182:183], 0
	v_mfma_f32_16x16x32_fp8_fp8 v[96:99], v[16:17], v[182:183], 0
	v_mfma_f32_16x16x32_fp8_fp8 v[84:87], v[4:5], v[184:185], v[84:87]
	v_mfma_f32_16x16x32_fp8_fp8 v[88:91], v[8:9], v[184:185], v[88:91]
	v_mfma_f32_16x16x32_fp8_fp8 v[92:95], v[14:15], v[184:185], v[92:95]
	v_mfma_f32_16x16x32_fp8_fp8 v[96:99], v[18:19], v[184:185], v[96:99]
	v_and_b32_e32 v199, s29, v244
	s_cmp_eq_u32 s14, 1
	v_cmp_ne_u32_e32 vcc, 0, v199
	s_cbranch_scc1 .Lbm2_Ag2_near
	v_add_f32_e32 v200, v81, v192
	v_cndmask_b32_e32 v200, v77, v200, vcc
	s_cmp_eq_u32 s35, 0
	s_cbranch_scc1 .Lbm2_Ag2_first
	v_pk_fma_f32 v[84:85], v[84:85], s[16:17], v[200:201] op_sel_hi:[1,1,0]
	v_pk_fma_f32 v[86:87], v[86:87], s[16:17], v[200:201] op_sel_hi:[1,1,0]
	v_pk_fma_f32 v[88:89], v[88:89], s[16:17], v[200:201] op_sel_hi:[1,1,0]
	v_pk_fma_f32 v[90:91], v[90:91], s[16:17], v[200:201] op_sel_hi:[1,1,0]
	v_exp_f32_e32 v84, v84
	v_exp_f32_e32 v85, v85
	v_exp_f32_e32 v86, v86
	v_exp_f32_e32 v87, v87
	v_pk_fma_f32 v[92:93], v[92:93], s[16:17], v[200:201] op_sel_hi:[1,1,0]
	v_pk_fma_f32 v[94:95], v[94:95], s[16:17], v[200:201] op_sel_hi:[1,1,0]
	v_exp_f32_e32 v88, v88
	v_exp_f32_e32 v89, v89
	v_exp_f32_e32 v90, v90
	v_exp_f32_e32 v91, v91
	v_pk_fma_f32 v[96:97], v[96:97], s[16:17], v[200:201] op_sel_hi:[1,1,0]
	v_pk_fma_f32 v[98:99], v[98:99], s[16:17], v[200:201] op_sel_hi:[1,1,0]
	v_exp_f32_e32 v92, v92
	v_exp_f32_e32 v93, v93
	v_exp_f32_e32 v94, v94
	v_exp_f32_e32 v95, v95
	s_nop 0
	v_exp_f32_e32 v96, v96
	v_exp_f32_e32 v97, v97
	v_exp_f32_e32 v98, v98
	v_exp_f32_e32 v99, v99
	v_pk_add_f32 v[248:249], v[84:85], v[86:87]
	v_pk_add_f32 v[82:83], v[88:89], v[90:91]
	v_pk_add_f32 v[172:173], v[92:93], v[94:95]
	v_pk_add_f32 v[202:203], v[96:97], v[98:99]
	v_cvt_pk_fp8_f32 v84, v84, v85
	v_cvt_pk_fp8_f32 v85, v88, v89
	v_pk_add_f32 v[248:249], v[248:249], v[82:83]
	v_pk_add_f32 v[172:173], v[172:173], v[202:203]
	v_cvt_pk_fp8_f32 v84, v86, v87 op_sel:[0,0,1]
	v_cvt_pk_fp8_f32 v85, v90, v91 op_sel:[0,0,1]
	v_pk_add_f32 v[248:249], v[248:249], v[172:173]
	v_cvt_pk_fp8_f32 v86, v92, v93
	v_cvt_pk_fp8_f32 v87, v96, v97
	v_add_f32_e32 v248, v248, v249
	v_cvt_pk_fp8_f32 v86, v94, v95 op_sel:[0,0,1]
	v_cvt_pk_fp8_f32 v87, v98, v99 op_sel:[0,0,1]
	v_cmp_lt_f32_e32 vcc, 0x43800000, v248
	s_cbranch_vccnz .Lbm2_Ag2_redo
	v_add_f32_e32 v196, v196, v248
	s_waitcnt vmcnt(8)
	v_mfma_f32_16x16x32_fp8_fp8 v[132:135], v[36:37], v[84:85], v[132:135]
	v_mfma_f32_16x16x32_fp8_fp8 v[136:139], v[38:39], v[84:85], v[136:139]
	v_mfma_f32_16x16x32_fp8_fp8 v[140:143], v[40:41], v[84:85], v[140:143]
	v_mfma_f32_16x16x32_fp8_fp8 v[144:147], v[42:43], v[84:85], v[144:147]
	v_mfma_f32_16x16x32_fp8_fp8 v[132:135], v[44:45], v[86:87], v[132:135]
	v_mfma_f32_16x16x32_fp8_fp8 v[136:139], v[46:47], v[86:87], v[136:139]
	v_mfma_f32_16x16x32_fp8_fp8 v[140:143], v[48:49], v[86:87], v[140:143]
	v_mfma_f32_16x16x32_fp8_fp8 v[144:147], v[50:51], v[86:87], v[144:147]
	s_lshr_b32 s29, s48, 12
	s_cmp_eq_u32 s29, 0
	s_cbranch_scc1 .Lbm2_Ag3_skip
	s_branch .Lbm2_Ag2_skip

.Lbm2_Ag2_exp:
	v_exp_f32_e32 v84, v84
	v_exp_f32_e32 v85, v85
	v_exp_f32_e32 v86, v86
	v_exp_f32_e32 v87, v87
	v_exp_f32_e32 v88, v88
	v_exp_f32_e32 v89, v89
	v_exp_f32_e32 v90, v90
	v_exp_f32_e32 v91, v91
	v_exp_f32_e32 v92, v92
	v_exp_f32_e32 v93, v93
	v_exp_f32_e32 v94, v94
	v_exp_f32_e32 v95, v95
	v_exp_f32_e32 v96, v96
	v_exp_f32_e32 v97, v97
	v_exp_f32_e32 v98, v98
	v_exp_f32_e32 v99, v99
	v_pk_add_f32 v[248:249], v[84:85], v[86:87]
	v_pk_add_f32 v[248:249], v[248:249], v[88:89]
	v_pk_add_f32 v[248:249], v[248:249], v[90:91]
	v_pk_add_f32 v[248:249], v[248:249], v[92:93]
	v_pk_add_f32 v[248:249], v[248:249], v[94:95]
	v_pk_add_f32 v[248:249], v[248:249], v[96:97]
	v_pk_add_f32 v[248:249], v[248:249], v[98:99]
	v_cvt_pk_fp8_f32 v84, v84, v85
	v_cvt_pk_fp8_f32 v85, v88, v89
	v_cvt_pk_fp8_f32 v84, v86, v87 op_sel:[0,0,1]
	v_cvt_pk_fp8_f32 v85, v90, v91 op_sel:[0,0,1]
	v_cvt_pk_fp8_f32 v86, v92, v93
	v_cvt_pk_fp8_f32 v87, v96, v97
	v_cvt_pk_fp8_f32 v86, v94, v95 op_sel:[0,0,1]
	v_cvt_pk_fp8_f32 v87, v98, v99 op_sel:[0,0,1]
	v_add_f32_e32 v248, v248, v249
	v_add_f32_e32 v196, v196, v248
	s_waitcnt vmcnt(8)
	v_mfma_f32_16x16x32_fp8_fp8 v[132:135], v[36:37], v[84:85], v[132:135]
	v_mfma_f32_16x16x32_fp8_fp8 v[136:139], v[38:39], v[84:85], v[136:139]
	v_mfma_f32_16x16x32_fp8_fp8 v[140:143], v[40:41], v[84:85], v[140:143]
	v_mfma_f32_16x16x32_fp8_fp8 v[144:147], v[42:43], v[84:85], v[144:147]
	v_mfma_f32_16x16x32_fp8_fp8 v[132:135], v[44:45], v[86:87], v[132:135]
	v_mfma_f32_16x16x32_fp8_fp8 v[136:139], v[46:47], v[86:87], v[136:139]
	v_mfma_f32_16x16x32_fp8_fp8 v[140:143], v[48:49], v[86:87], v[140:143]
	v_mfma_f32_16x16x32_fp8_fp8 v[144:147], v[50:51], v[86:87], v[144:147]
	s_lshr_b32 s29, s48, 12
	s_cmp_eq_u32 s29, 0
	s_cbranch_scc1 .Lbm2_Ag3_skip
	s_branch .Lbm2_Ag2_skip

.Lbm2_blkB:
	s_lshl_b32 s12, s15, 12
	s_add_u32 s30, s46, s12
	s_addc_u32 s31, s47, 0
	global_load_dwordx4 v[2:5], v79, s[30:31]
	global_load_dwordx4 v[6:9], v79, s[30:31] offset:1024
	global_load_dwordx4 v[12:15], v79, s[30:31] offset:2048
	global_load_dwordx4 v[16:19], v79, s[30:31] offset:3072
	s_lshl_b32 s12, s15, 12
	s_add_u32 s30, s62, s12
	s_addc_u32 s31, s63, 0
	global_load_dwordx4 v[36:39], v79, s[30:31]
	global_load_dwordx4 v[40:43], v79, s[30:31] offset:1024
	global_load_dwordx4 v[44:47], v79, s[30:31] offset:2048
	global_load_dwordx4 v[48:51], v79, s[30:31] offset:3072
	s_add_i32 s14, s35, 2
	s_add_i32 s13, s25, -1
	s_min_i32 s14, s14, s13
	s_lshl_b32 s13, s14, 2
	s_add_i32 s13, s13, s96
	v_mov_b32_e32 v76, s13
	ds_read_b32 v76, v76 offset:16384
	s_cmp_ge_i32 s54, s21
	s_cselect_b32 s14, 1, 0
	s_bfe_u32 s29, s48, 0x40000
	s_cmp_eq_u32 s29, 0
	s_cbranch_scc1 .Lbm2_Bg0_skip
	s_waitcnt vmcnt(12)
	v_mfma_f32_16x16x32_fp8_fp8 v[84:87], v[20:21], v[164:165], 0
	v_mfma_f32_16x16x32_fp8_fp8 v[88:91], v[24:25], v[164:165], 0
	v_mfma_f32_16x16x32_fp8_fp8 v[92:95], v[28:29], v[164:165], 0
	v_mfma_f32_16x16x32_fp8_fp8 v[96:99], v[32:33], v[164:165], 0
	v_mfma_f32_16x16x32_fp8_fp8 v[84:87], v[22:23], v[166:167], v[84:87]
	v_mfma_f32_16x16x32_fp8_fp8 v[88:91], v[26:27], v[166:167], v[88:91]
	v_mfma_f32_16x16x32_fp8_fp8 v[92:95], v[30:31], v[166:167], v[92:95]
	v_mfma_f32_16x16x32_fp8_fp8 v[96:99], v[34:35], v[166:167], v[96:99]
	v_and_b32_e32 v199, s29, v244
	s_cmp_eq_u32 s14, 1
	v_cmp_ne_u32_e32 vcc, 0, v199
	s_cbranch_scc1 .Lbm2_Bg0_near
	v_add_f32_e32 v200, v81, v190
	v_cndmask_b32_e32 v200, v77, v200, vcc
	s_cmp_eq_u32 s35, 0
	s_cbranch_scc1 .Lbm2_Bg0_first
	v_pk_fma_f32 v[84:85], v[84:85], s[16:17], v[200:201] op_sel_hi:[1,1,0]
	v_pk_fma_f32 v[86:87], v[86:87], s[16:17], v[200:201] op_sel_hi:[1,1,0]
	v_pk_fma_f32 v[88:89], v[88:89], s[16:17], v[200:201] op_sel_hi:[1,1,0]
	v_pk_fma_f32 v[90:91], v[90:91], s[16:17], v[200:201] op_sel_hi:[1,1,0]
	v_exp_f32_e32 v84, v84
	v_exp_f32_e32 v85, v85
	v_exp_f32_e32 v86, v86
	v_exp_f32_e32 v87, v87
	v_pk_fma_f32 v[92:93], v[92:93], s[16:17], v[200:201] op_sel_hi:[1,1,0]
	v_pk_fma_f32 v[94:95], v[94:95], s[16:17], v[200:201] op_sel_hi:[1,1,0]
	v_exp_f32_e32 v88, v88
	v_exp_f32_e32 v89, v89
	v_exp_f32_e32 v90, v90
	v_exp_f32_e32 v91, v91
	v_pk_fma_f32 v[96:97], v[96:97], s[16:17], v[200:201] op_sel_hi:[1,1,0]
	v_pk_fma_f32 v[98:99], v[98:99], s[16:17], v[200:201] op_sel_hi:[1,1,0]
	v_exp_f32_e32 v92, v92
	v_exp_f32_e32 v93, v93
	v_exp_f32_e32 v94, v94
	v_exp_f32_e32 v95, v95
	s_nop 0
	v_exp_f32_e32 v96, v96
	v_exp_f32_e32 v97, v97
	v_exp_f32_e32 v98, v98
	v_exp_f32_e32 v99, v99
	v_pk_add_f32 v[248:249], v[84:85], v[86:87]
	v_pk_add_f32 v[82:83], v[88:89], v[90:91]
	v_pk_add_f32 v[172:173], v[92:93], v[94:95]
	v_pk_add_f32 v[202:203], v[96:97], v[98:99]
	v_cvt_pk_fp8_f32 v84, v84, v85
	v_cvt_pk_fp8_f32 v85, v88, v89
	v_pk_add_f32 v[248:249], v[248:249], v[82:83]
	v_pk_add_f32 v[172:173], v[172:173], v[202:203]
	v_cvt_pk_fp8_f32 v84, v86, v87 op_sel:[0,0,1]
	v_cvt_pk_fp8_f32 v85, v90, v91 op_sel:[0,0,1]
	v_pk_add_f32 v[248:249], v[248:249], v[172:173]
	v_cvt_pk_fp8_f32 v86, v92, v93
	v_cvt_pk_fp8_f32 v87, v96, v97
	v_add_f32_e32 v248, v248, v249
	v_cvt_pk_fp8_f32 v86, v94, v95 op_sel:[0,0,1]
	v_cvt_pk_fp8_f32 v87, v98, v99 op_sel:[0,0,1]
	v_cmp_lt_f32_e32 vcc, 0x43800000, v248
	s_cbranch_vccnz .Lbm2_Bg0_redo
	v_add_f32_e32 v194, v194, v248
	s_waitcnt vmcnt(8)
	v_mfma_f32_16x16x32_fp8_fp8 v[100:103], v[52:53], v[84:85], v[100:103]
	v_mfma_f32_16x16x32_fp8_fp8 v[104:107], v[54:55], v[84:85], v[104:107]
	v_mfma_f32_16x16x32_fp8_fp8 v[108:111], v[56:57], v[84:85], v[108:111]
	v_mfma_f32_16x16x32_fp8_fp8 v[112:115], v[58:59], v[84:85], v[112:115]
	v_mfma_f32_16x16x32_fp8_fp8 v[100:103], v[60:61], v[86:87], v[100:103]
	v_mfma_f32_16x16x32_fp8_fp8 v[104:107], v[62:63], v[86:87], v[104:107]
	v_mfma_f32_16x16x32_fp8_fp8 v[108:111], v[64:65], v[86:87], v[108:111]
	v_mfma_f32_16x16x32_fp8_fp8 v[112:115], v[66:67], v[86:87], v[112:115]
	s_lshr_b32 s29, s48, 4
	s_cmp_eq_u32 s29, 0
	s_cbranch_scc1 .Lbm2_Bg3_skip
	s_branch .Lbm2_Bg0_skip

.Lbm2_Bg0_exp:
	v_exp_f32_e32 v84, v84
	v_exp_f32_e32 v85, v85
	v_exp_f32_e32 v86, v86
	v_exp_f32_e32 v87, v87
	v_exp_f32_e32 v88, v88
	v_exp_f32_e32 v89, v89
	v_exp_f32_e32 v90, v90
	v_exp_f32_e32 v91, v91
	v_exp_f32_e32 v92, v92
	v_exp_f32_e32 v93, v93
	v_exp_f32_e32 v94, v94
	v_exp_f32_e32 v95, v95
	v_exp_f32_e32 v96, v96
	v_exp_f32_e32 v97, v97
	v_exp_f32_e32 v98, v98
	v_exp_f32_e32 v99, v99
	v_pk_add_f32 v[248:249], v[84:85], v[86:87]
	v_pk_add_f32 v[248:249], v[248:249], v[88:89]
	v_pk_add_f32 v[248:249], v[248:249], v[90:91]
	v_pk_add_f32 v[248:249], v[248:249], v[92:93]
	v_pk_add_f32 v[248:249], v[248:249], v[94:95]
	v_pk_add_f32 v[248:249], v[248:249], v[96:97]
	v_pk_add_f32 v[248:249], v[248:249], v[98:99]
	v_cvt_pk_fp8_f32 v84, v84, v85
	v_cvt_pk_fp8_f32 v85, v88, v89
	v_cvt_pk_fp8_f32 v84, v86, v87 op_sel:[0,0,1]
	v_cvt_pk_fp8_f32 v85, v90, v91 op_sel:[0,0,1]
	v_cvt_pk_fp8_f32 v86, v92, v93
	v_cvt_pk_fp8_f32 v87, v96, v97
	v_cvt_pk_fp8_f32 v86, v94, v95 op_sel:[0,0,1]
	v_cvt_pk_fp8_f32 v87, v98, v99 op_sel:[0,0,1]
	v_add_f32_e32 v248, v248, v249
	v_add_f32_e32 v194, v194, v248
	s_waitcnt vmcnt(8)
	v_mfma_f32_16x16x32_fp8_fp8 v[100:103], v[52:53], v[84:85], v[100:103]
	v_mfma_f32_16x16x32_fp8_fp8 v[104:107], v[54:55], v[84:85], v[104:107]
	v_mfma_f32_16x16x32_fp8_fp8 v[108:111], v[56:57], v[84:85], v[108:111]
	v_mfma_f32_16x16x32_fp8_fp8 v[112:115], v[58:59], v[84:85], v[112:115]
	v_mfma_f32_16x16x32_fp8_fp8 v[100:103], v[60:61], v[86:87], v[100:103]
	v_mfma_f32_16x16x32_fp8_fp8 v[104:107], v[62:63], v[86:87], v[104:107]
	v_mfma_f32_16x16x32_fp8_fp8 v[108:111], v[64:65], v[86:87], v[108:111]
	v_mfma_f32_16x16x32_fp8_fp8 v[112:115], v[66:67], v[86:87], v[112:115]
	s_lshr_b32 s29, s48, 4
	s_cmp_eq_u32 s29, 0
	s_cbranch_scc1 .Lbm2_Bg3_skip
	s_branch .Lbm2_Bg0_skip

.Lbm2_Bg0_skip:
	s_bfe_u32 s29, s48, 0x40004
	s_cmp_eq_u32 s29, 0
	s_cbranch_scc1 .Lbm2_Bg1_skip
	s_waitcnt vmcnt(12)
	v_mfma_f32_16x16x32_fp8_fp8 v[84:87], v[20:21], v[168:169], 0
	v_mfma_f32_16x16x32_fp8_fp8 v[88:91], v[24:25], v[168:169], 0
	v_mfma_f32_16x16x32_fp8_fp8 v[92:95], v[28:29], v[168:169], 0
	v_mfma_f32_16x16x32_fp8_fp8 v[96:99], v[32:33], v[168:169], 0
	v_mfma_f32_16x16x32_fp8_fp8 v[84:87], v[22:23], v[170:171], v[84:87]
	v_mfma_f32_16x16x32_fp8_fp8 v[88:91], v[26:27], v[170:171], v[88:91]
	v_mfma_f32_16x16x32_fp8_fp8 v[92:95], v[30:31], v[170:171], v[92:95]
	v_mfma_f32_16x16x32_fp8_fp8 v[96:99], v[34:35], v[170:171], v[96:99]
	v_and_b32_e32 v199, s29, v244
	s_cmp_eq_u32 s14, 1
	v_cmp_ne_u32_e32 vcc, 0, v199
	s_cbranch_scc1 .Lbm2_Bg1_near
	v_add_f32_e32 v200, v81, v191
	v_cndmask_b32_e32 v200, v77, v200, vcc
	s_cmp_eq_u32 s35, 0
	s_cbranch_scc1 .Lbm2_Bg1_first
	v_pk_fma_f32 v[84:85], v[84:85], s[16:17], v[200:201] op_sel_hi:[1,1,0]
	v_pk_fma_f32 v[86:87], v[86:87], s[16:17], v[200:201] op_sel_hi:[1,1,0]
	v_pk_fma_f32 v[88:89], v[88:89], s[16:17], v[200:201] op_sel_hi:[1,1,0]
	v_pk_fma_f32 v[90:91], v[90:91], s[16:17], v[200:201] op_sel_hi:[1,1,0]
	v_exp_f32_e32 v84, v84
	v_exp_f32_e32 v85, v85
	v_exp_f32_e32 v86, v86
	v_exp_f32_e32 v87, v87
	v_pk_fma_f32 v[92:93], v[92:93], s[16:17], v[200:201] op_sel_hi:[1,1,0]
	v_pk_fma_f32 v[94:95], v[94:95], s[16:17], v[200:201] op_sel_hi:[1,1,0]
	v_exp_f32_e32 v88, v88
	v_exp_f32_e32 v89, v89
	v_exp_f32_e32 v90, v90
	v_exp_f32_e32 v91, v91
	v_pk_fma_f32 v[96:97], v[96:97], s[16:17], v[200:201] op_sel_hi:[1,1,0]
	v_pk_fma_f32 v[98:99], v[98:99], s[16:17], v[200:201] op_sel_hi:[1,1,0]
	v_exp_f32_e32 v92, v92
	v_exp_f32_e32 v93, v93
	v_exp_f32_e32 v94, v94
	v_exp_f32_e32 v95, v95
	s_nop 0
	v_exp_f32_e32 v96, v96
	v_exp_f32_e32 v97, v97
	v_exp_f32_e32 v98, v98
	v_exp_f32_e32 v99, v99
	v_pk_add_f32 v[248:249], v[84:85], v[86:87]
	v_pk_add_f32 v[82:83], v[88:89], v[90:91]
	v_pk_add_f32 v[172:173], v[92:93], v[94:95]
	v_pk_add_f32 v[202:203], v[96:97], v[98:99]
	v_cvt_pk_fp8_f32 v84, v84, v85
	v_cvt_pk_fp8_f32 v85, v88, v89
	v_pk_add_f32 v[248:249], v[248:249], v[82:83]
	v_pk_add_f32 v[172:173], v[172:173], v[202:203]
	v_cvt_pk_fp8_f32 v84, v86, v87 op_sel:[0,0,1]
	v_cvt_pk_fp8_f32 v85, v90, v91 op_sel:[0,0,1]
	v_pk_add_f32 v[248:249], v[248:249], v[172:173]
	v_cvt_pk_fp8_f32 v86, v92, v93
	v_cvt_pk_fp8_f32 v87, v96, v97
	v_add_f32_e32 v248, v248, v249
	v_cvt_pk_fp8_f32 v86, v94, v95 op_sel:[0,0,1]
	v_cvt_pk_fp8_f32 v87, v98, v99 op_sel:[0,0,1]
	v_cmp_lt_f32_e32 vcc, 0x43800000, v248
	s_cbranch_vccnz .Lbm2_Bg1_redo
	v_add_f32_e32 v195, v195, v248
	s_waitcnt vmcnt(8)
	v_mfma_f32_16x16x32_fp8_fp8 v[116:119], v[52:53], v[84:85], v[116:119]
	v_mfma_f32_16x16x32_fp8_fp8 v[120:123], v[54:55], v[84:85], v[120:123]
	v_mfma_f32_16x16x32_fp8_fp8 v[124:127], v[56:57], v[84:85], v[124:127]
	v_mfma_f32_16x16x32_fp8_fp8 v[128:131], v[58:59], v[84:85], v[128:131]
	v_mfma_f32_16x16x32_fp8_fp8 v[116:119], v[60:61], v[86:87], v[116:119]
	v_mfma_f32_16x16x32_fp8_fp8 v[120:123], v[62:63], v[86:87], v[120:123]
	v_mfma_f32_16x16x32_fp8_fp8 v[124:127], v[64:65], v[86:87], v[124:127]
	v_mfma_f32_16x16x32_fp8_fp8 v[128:131], v[66:67], v[86:87], v[128:131]
	s_lshr_b32 s29, s48, 8
	s_cmp_eq_u32 s29, 0
	s_cbranch_scc1 .Lbm2_Bg3_skip
	s_branch .Lbm2_Bg1_skip

.Lbm2_Bg1_exp:
	v_exp_f32_e32 v84, v84
	v_exp_f32_e32 v85, v85
	v_exp_f32_e32 v86, v86
	v_exp_f32_e32 v87, v87
	v_exp_f32_e32 v88, v88
	v_exp_f32_e32 v89, v89
	v_exp_f32_e32 v90, v90
	v_exp_f32_e32 v91, v91
	v_exp_f32_e32 v92, v92
	v_exp_f32_e32 v93, v93
	v_exp_f32_e32 v94, v94
	v_exp_f32_e32 v95, v95
	v_exp_f32_e32 v96, v96
	v_exp_f32_e32 v97, v97
	v_exp_f32_e32 v98, v98
	v_exp_f32_e32 v99, v99
	v_pk_add_f32 v[248:249], v[84:85], v[86:87]
	v_pk_add_f32 v[248:249], v[248:249], v[88:89]
	v_pk_add_f32 v[248:249], v[248:249], v[90:91]
	v_pk_add_f32 v[248:249], v[248:249], v[92:93]
	v_pk_add_f32 v[248:249], v[248:249], v[94:95]
	v_pk_add_f32 v[248:249], v[248:249], v[96:97]
	v_pk_add_f32 v[248:249], v[248:249], v[98:99]
	v_cvt_pk_fp8_f32 v84, v84, v85
	v_cvt_pk_fp8_f32 v85, v88, v89
	v_cvt_pk_fp8_f32 v84, v86, v87 op_sel:[0,0,1]
	v_cvt_pk_fp8_f32 v85, v90, v91 op_sel:[0,0,1]
	v_cvt_pk_fp8_f32 v86, v92, v93
	v_cvt_pk_fp8_f32 v87, v96, v97
	v_cvt_pk_fp8_f32 v86, v94, v95 op_sel:[0,0,1]
	v_cvt_pk_fp8_f32 v87, v98, v99 op_sel:[0,0,1]
	v_add_f32_e32 v248, v248, v249
	v_add_f32_e32 v195, v195, v248
	s_waitcnt vmcnt(8)
	v_mfma_f32_16x16x32_fp8_fp8 v[116:119], v[52:53], v[84:85], v[116:119]
	v_mfma_f32_16x16x32_fp8_fp8 v[120:123], v[54:55], v[84:85], v[120:123]
	v_mfma_f32_16x16x32_fp8_fp8 v[124:127], v[56:57], v[84:85], v[124:127]
	v_mfma_f32_16x16x32_fp8_fp8 v[128:131], v[58:59], v[84:85], v[128:131]
	v_mfma_f32_16x16x32_fp8_fp8 v[116:119], v[60:61], v[86:87], v[116:119]
	v_mfma_f32_16x16x32_fp8_fp8 v[120:123], v[62:63], v[86:87], v[120:123]
	v_mfma_f32_16x16x32_fp8_fp8 v[124:127], v[64:65], v[86:87], v[124:127]
	v_mfma_f32_16x16x32_fp8_fp8 v[128:131], v[66:67], v[86:87], v[128:131]
	s_lshr_b32 s29, s48, 8
	s_cmp_eq_u32 s29, 0
	s_cbranch_scc1 .Lbm2_Bg3_skip
	s_branch .Lbm2_Bg1_skip

.Lbm2_Bg1_skip:
	s_bfe_u32 s29, s48, 0x40008
	s_cmp_eq_u32 s29, 0
	s_cbranch_scc1 .Lbm2_Bg2_skip
	s_waitcnt vmcnt(12)
	v_mfma_f32_16x16x32_fp8_fp8 v[84:87], v[20:21], v[182:183], 0
	v_mfma_f32_16x16x32_fp8_fp8 v[88:91], v[24:25], v[182:183], 0
	v_mfma_f32_16x16x32_fp8_fp8 v[92:95], v[28:29], v[182:183], 0
	v_mfma_f32_16x16x32_fp8_fp8 v[96:99], v[32:33], v[182:183], 0
	v_mfma_f32_16x16x32_fp8_fp8 v[84:87], v[22:23], v[184:185], v[84:87]
	v_mfma_f32_16x16x32_fp8_fp8 v[88:91], v[26:27], v[184:185], v[88:91]
	v_mfma_f32_16x16x32_fp8_fp8 v[92:95], v[30:31], v[184:185], v[92:95]
	v_mfma_f32_16x16x32_fp8_fp8 v[96:99], v[34:35], v[184:185], v[96:99]
	v_and_b32_e32 v199, s29, v244
	s_cmp_eq_u32 s14, 1
	v_cmp_ne_u32_e32 vcc, 0, v199
	s_cbranch_scc1 .Lbm2_Bg2_near
	v_add_f32_e32 v200, v81, v192
	v_cndmask_b32_e32 v200, v77, v200, vcc
	s_cmp_eq_u32 s35, 0
	s_cbranch_scc1 .Lbm2_Bg2_first
	v_pk_fma_f32 v[84:85], v[84:85], s[16:17], v[200:201] op_sel_hi:[1,1,0]
	v_pk_fma_f32 v[86:87], v[86:87], s[16:17], v[200:201] op_sel_hi:[1,1,0]
	v_pk_fma_f32 v[88:89], v[88:89], s[16:17], v[200:201] op_sel_hi:[1,1,0]
	v_pk_fma_f32 v[90:91], v[90:91], s[16:17], v[200:201] op_sel_hi:[1,1,0]
	v_exp_f32_e32 v84, v84
	v_exp_f32_e32 v85, v85
	v_exp_f32_e32 v86, v86
	v_exp_f32_e32 v87, v87
	v_pk_fma_f32 v[92:93], v[92:93], s[16:17], v[200:201] op_sel_hi:[1,1,0]
	v_pk_fma_f32 v[94:95], v[94:95], s[16:17], v[200:201] op_sel_hi:[1,1,0]
	v_exp_f32_e32 v88, v88
	v_exp_f32_e32 v89, v89
	v_exp_f32_e32 v90, v90
	v_exp_f32_e32 v91, v91
	v_pk_fma_f32 v[96:97], v[96:97], s[16:17], v[200:201] op_sel_hi:[1,1,0]
	v_pk_fma_f32 v[98:99], v[98:99], s[16:17], v[200:201] op_sel_hi:[1,1,0]
	v_exp_f32_e32 v92, v92
	v_exp_f32_e32 v93, v93
	v_exp_f32_e32 v94, v94
	v_exp_f32_e32 v95, v95
	s_nop 0
	v_exp_f32_e32 v96, v96
	v_exp_f32_e32 v97, v97
	v_exp_f32_e32 v98, v98
	v_exp_f32_e32 v99, v99
	v_pk_add_f32 v[248:249], v[84:85], v[86:87]
	v_pk_add_f32 v[82:83], v[88:89], v[90:91]
	v_pk_add_f32 v[172:173], v[92:93], v[94:95]
	v_pk_add_f32 v[202:203], v[96:97], v[98:99]
	v_cvt_pk_fp8_f32 v84, v84, v85
	v_cvt_pk_fp8_f32 v85, v88, v89
	v_pk_add_f32 v[248:249], v[248:249], v[82:83]
	v_pk_add_f32 v[172:173], v[172:173], v[202:203]
	v_cvt_pk_fp8_f32 v84, v86, v87 op_sel:[0,0,1]
	v_cvt_pk_fp8_f32 v85, v90, v91 op_sel:[0,0,1]
	v_pk_add_f32 v[248:249], v[248:249], v[172:173]
	v_cvt_pk_fp8_f32 v86, v92, v93
	v_cvt_pk_fp8_f32 v87, v96, v97
	v_add_f32_e32 v248, v248, v249
	v_cvt_pk_fp8_f32 v86, v94, v95 op_sel:[0,0,1]
	v_cvt_pk_fp8_f32 v87, v98, v99 op_sel:[0,0,1]
	v_cmp_lt_f32_e32 vcc, 0x43800000, v248
	s_cbranch_vccnz .Lbm2_Bg2_redo
	v_add_f32_e32 v196, v196, v248
	s_waitcnt vmcnt(8)
	v_mfma_f32_16x16x32_fp8_fp8 v[132:135], v[52:53], v[84:85], v[132:135]
	v_mfma_f32_16x16x32_fp8_fp8 v[136:139], v[54:55], v[84:85], v[136:139]
	v_mfma_f32_16x16x32_fp8_fp8 v[140:143], v[56:57], v[84:85], v[140:143]
	v_mfma_f32_16x16x32_fp8_fp8 v[144:147], v[58:59], v[84:85], v[144:147]
	v_mfma_f32_16x16x32_fp8_fp8 v[132:135], v[60:61], v[86:87], v[132:135]
	v_mfma_f32_16x16x32_fp8_fp8 v[136:139], v[62:63], v[86:87], v[136:139]
	v_mfma_f32_16x16x32_fp8_fp8 v[140:143], v[64:65], v[86:87], v[140:143]
	v_mfma_f32_16x16x32_fp8_fp8 v[144:147], v[66:67], v[86:87], v[144:147]
	s_lshr_b32 s29, s48, 12
	s_cmp_eq_u32 s29, 0
	s_cbranch_scc1 .Lbm2_Bg3_skip
	s_branch .Lbm2_Bg2_skip

.Lbm2_Bg2_exp:
	v_exp_f32_e32 v84, v84
	v_exp_f32_e32 v85, v85
	v_exp_f32_e32 v86, v86
	v_exp_f32_e32 v87, v87
	v_exp_f32_e32 v88, v88
	v_exp_f32_e32 v89, v89
	v_exp_f32_e32 v90, v90
	v_exp_f32_e32 v91, v91
	v_exp_f32_e32 v92, v92
	v_exp_f32_e32 v93, v93
	v_exp_f32_e32 v94, v94
	v_exp_f32_e32 v95, v95
	v_exp_f32_e32 v96, v96
	v_exp_f32_e32 v97, v97
	v_exp_f32_e32 v98, v98
	v_exp_f32_e32 v99, v99
	v_pk_add_f32 v[248:249], v[84:85], v[86:87]
	v_pk_add_f32 v[248:249], v[248:249], v[88:89]
	v_pk_add_f32 v[248:249], v[248:249], v[90:91]
	v_pk_add_f32 v[248:249], v[248:249], v[92:93]
	v_pk_add_f32 v[248:249], v[248:249], v[94:95]
	v_pk_add_f32 v[248:249], v[248:249], v[96:97]
	v_pk_add_f32 v[248:249], v[248:249], v[98:99]
	v_cvt_pk_fp8_f32 v84, v84, v85
	v_cvt_pk_fp8_f32 v85, v88, v89
	v_cvt_pk_fp8_f32 v84, v86, v87 op_sel:[0,0,1]
	v_cvt_pk_fp8_f32 v85, v90, v91 op_sel:[0,0,1]
	v_cvt_pk_fp8_f32 v86, v92, v93
	v_cvt_pk_fp8_f32 v87, v96, v97
	v_cvt_pk_fp8_f32 v86, v94, v95 op_sel:[0,0,1]
	v_cvt_pk_fp8_f32 v87, v98, v99 op_sel:[0,0,1]
	v_add_f32_e32 v248, v248, v249
	v_add_f32_e32 v196, v196, v248
	s_waitcnt vmcnt(8)
	v_mfma_f32_16x16x32_fp8_fp8 v[132:135], v[52:53], v[84:85], v[132:135]
	v_mfma_f32_16x16x32_fp8_fp8 v[136:139], v[54:55], v[84:85], v[136:139]
	v_mfma_f32_16x16x32_fp8_fp8 v[140:143], v[56:57], v[84:85], v[140:143]
	v_mfma_f32_16x16x32_fp8_fp8 v[144:147], v[58:59], v[84:85], v[144:147]
	v_mfma_f32_16x16x32_fp8_fp8 v[132:135], v[60:61], v[86:87], v[132:135]
	v_mfma_f32_16x16x32_fp8_fp8 v[136:139], v[62:63], v[86:87], v[136:139]
	v_mfma_f32_16x16x32_fp8_fp8 v[140:143], v[64:65], v[86:87], v[140:143]
	v_mfma_f32_16x16x32_fp8_fp8 v[144:147], v[66:67], v[86:87], v[144:147]
	s_lshr_b32 s29, s48, 12
	s_cmp_eq_u32 s29, 0
	s_cbranch_scc1 .Lbm2_Bg3_skip
	s_branch .Lbm2_Bg2_skip

.Lbm3_nostag:
.Lbm3_blkA:
	s_lshl_b32 s29, s27, 12
	s_add_u32 s30, s40, s29
	s_addc_u32 s31, s41, 0
	global_load_dwordx4 v[20:23], v79, s[30:31]
	global_load_dwordx4 v[24:27], v79, s[30:31] offset:1024
	global_load_dwordx4 v[28:31], v79, s[30:31] offset:2048
	global_load_dwordx4 v[32:35], v79, s[30:31] offset:3072
	s_lshl_b32 s29, s27, 12
	s_add_u32 s30, s62, s29
	s_addc_u32 s31, s63, 0
	global_load_dwordx4 v[52:55], v79, s[30:31]
	global_load_dwordx4 v[56:59], v79, s[30:31] offset:1024
	global_load_dwordx4 v[60:63], v79, s[30:31] offset:2048
	global_load_dwordx4 v[64:67], v79, s[30:31] offset:3072
	s_add_i32 s50, s35, 2
	s_add_i32 s9, s25, -1
	s_min_i32 s50, s50, s9
	s_lshl_b32 s9, s50, 2
	s_add_i32 s9, s9, s46
	v_mov_b32_e32 v76, s9
	ds_read_b32 v76, v76 offset:16384
	s_cmp_ge_i32 s38, s21
	s_cselect_b32 s50, 1, 0
	s_bfe_u32 s29, s48, 0x40000
	s_cmp_eq_u32 s29, 0
	s_cbranch_scc1 .Lbm3_Ag0_skip
	s_waitcnt vmcnt(12)
	v_mfma_f32_16x16x32_fp8_fp8 v[84:87], v[2:3], v[164:165], 0
	v_mfma_f32_16x16x32_fp8_fp8 v[88:91], v[6:7], v[164:165], 0
	v_mfma_f32_16x16x32_fp8_fp8 v[92:95], v[12:13], v[164:165], 0
	v_mfma_f32_16x16x32_fp8_fp8 v[96:99], v[16:17], v[164:165], 0
	v_mfma_f32_16x16x32_fp8_fp8 v[84:87], v[4:5], v[166:167], v[84:87]
	v_mfma_f32_16x16x32_fp8_fp8 v[88:91], v[8:9], v[166:167], v[88:91]
	v_mfma_f32_16x16x32_fp8_fp8 v[92:95], v[14:15], v[166:167], v[92:95]
	v_mfma_f32_16x16x32_fp8_fp8 v[96:99], v[18:19], v[166:167], v[96:99]
	v_and_b32_e32 v199, s29, v244
	s_cmp_eq_u32 s50, 1
	v_cmp_ne_u32_e32 vcc, 0, v199
	s_cbranch_scc1 .Lbm3_Ag0_near
	v_add_f32_e32 v200, v81, v190
	v_cndmask_b32_e32 v200, v77, v200, vcc
	s_cmp_eq_u32 s35, 0
	s_cbranch_scc1 .Lbm3_Ag0_first
	v_pk_fma_f32 v[84:85], v[84:85], s[10:11], v[200:201] op_sel_hi:[1,1,0]
	v_pk_fma_f32 v[86:87], v[86:87], s[10:11], v[200:201] op_sel_hi:[1,1,0]
	v_pk_fma_f32 v[88:89], v[88:89], s[10:11], v[200:201] op_sel_hi:[1,1,0]
	v_pk_fma_f32 v[90:91], v[90:91], s[10:11], v[200:201] op_sel_hi:[1,1,0]
	v_exp_f32_e32 v84, v84
	v_exp_f32_e32 v85, v85
	v_exp_f32_e32 v86, v86
	v_exp_f32_e32 v87, v87
	v_pk_fma_f32 v[92:93], v[92:93], s[10:11], v[200:201] op_sel_hi:[1,1,0]
	v_pk_fma_f32 v[94:95], v[94:95], s[10:11], v[200:201] op_sel_hi:[1,1,0]
	v_exp_f32_e32 v88, v88
	v_exp_f32_e32 v89, v89
	v_exp_f32_e32 v90, v90
	v_exp_f32_e32 v91, v91
	v_pk_fma_f32 v[96:97], v[96:97], s[10:11], v[200:201] op_sel_hi:[1,1,0]
	v_pk_fma_f32 v[98:99], v[98:99], s[10:11], v[200:201] op_sel_hi:[1,1,0]
	v_exp_f32_e32 v92, v92
	v_exp_f32_e32 v93, v93
	v_exp_f32_e32 v94, v94
	v_exp_f32_e32 v95, v95
	s_nop 0
	v_exp_f32_e32 v96, v96
	v_exp_f32_e32 v97, v97
	v_exp_f32_e32 v98, v98
	v_exp_f32_e32 v99, v99
	v_pk_add_f32 v[248:249], v[84:85], v[86:87]
	v_pk_add_f32 v[82:83], v[88:89], v[90:91]
	v_pk_add_f32 v[172:173], v[92:93], v[94:95]
	v_pk_add_f32 v[202:203], v[96:97], v[98:99]
	v_cvt_pk_fp8_f32 v84, v84, v85
	v_cvt_pk_fp8_f32 v85, v88, v89
	v_pk_add_f32 v[248:249], v[248:249], v[82:83]
	v_pk_add_f32 v[172:173], v[172:173], v[202:203]
	v_cvt_pk_fp8_f32 v84, v86, v87 op_sel:[0,0,1]
	v_cvt_pk_fp8_f32 v85, v90, v91 op_sel:[0,0,1]
	v_pk_add_f32 v[248:249], v[248:249], v[172:173]
	v_cvt_pk_fp8_f32 v86, v92, v93
	v_cvt_pk_fp8_f32 v87, v96, v97
	v_add_f32_e32 v248, v248, v249
	v_cvt_pk_fp8_f32 v86, v94, v95 op_sel:[0,0,1]
	v_cvt_pk_fp8_f32 v87, v98, v99 op_sel:[0,0,1]
	v_cmp_lt_f32_e32 vcc, 0x43800000, v248
	s_cbranch_vccnz .Lbm3_Ag0_redo
	v_add_f32_e32 v194, v194, v248
	s_waitcnt vmcnt(8)
	v_mfma_f32_16x16x32_fp8_fp8 v[100:103], v[36:37], v[84:85], v[100:103]
	v_mfma_f32_16x16x32_fp8_fp8 v[104:107], v[38:39], v[84:85], v[104:107]
	v_mfma_f32_16x16x32_fp8_fp8 v[108:111], v[40:41], v[84:85], v[108:111]
	v_mfma_f32_16x16x32_fp8_fp8 v[112:115], v[42:43], v[84:85], v[112:115]
	v_mfma_f32_16x16x32_fp8_fp8 v[100:103], v[44:45], v[86:87], v[100:103]
	v_mfma_f32_16x16x32_fp8_fp8 v[104:107], v[46:47], v[86:87], v[104:107]
	v_mfma_f32_16x16x32_fp8_fp8 v[108:111], v[48:49], v[86:87], v[108:111]
	v_mfma_f32_16x16x32_fp8_fp8 v[112:115], v[50:51], v[86:87], v[112:115]
	s_lshr_b32 s29, s48, 4
	s_cmp_eq_u32 s29, 0
	s_cbranch_scc1 .Lbm3_Ag3_skip
	s_branch .Lbm3_Ag0_skip

.Lbm3_Ag0_skip:
	s_bfe_u32 s29, s48, 0x40004
	s_cmp_eq_u32 s29, 0
	s_cbranch_scc1 .Lbm3_Ag1_skip
	s_waitcnt vmcnt(12)
	v_mfma_f32_16x16x32_fp8_fp8 v[84:87], v[2:3], v[168:169], 0
	v_mfma_f32_16x16x32_fp8_fp8 v[88:91], v[6:7], v[168:169], 0
	v_mfma_f32_16x16x32_fp8_fp8 v[92:95], v[12:13], v[168:169], 0
	v_mfma_f32_16x16x32_fp8_fp8 v[96:99], v[16:17], v[168:169], 0
	v_mfma_f32_16x16x32_fp8_fp8 v[84:87], v[4:5], v[170:171], v[84:87]
	v_mfma_f32_16x16x32_fp8_fp8 v[88:91], v[8:9], v[170:171], v[88:91]
	v_mfma_f32_16x16x32_fp8_fp8 v[92:95], v[14:15], v[170:171], v[92:95]
	v_mfma_f32_16x16x32_fp8_fp8 v[96:99], v[18:19], v[170:171], v[96:99]
	v_and_b32_e32 v199, s29, v244
	s_cmp_eq_u32 s50, 1
	v_cmp_ne_u32_e32 vcc, 0, v199
	s_cbranch_scc1 .Lbm3_Ag1_near
	v_add_f32_e32 v200, v81, v191
	v_cndmask_b32_e32 v200, v77, v200, vcc
	s_cmp_eq_u32 s35, 0
	s_cbranch_scc1 .Lbm3_Ag1_first
	v_pk_fma_f32 v[84:85], v[84:85], s[10:11], v[200:201] op_sel_hi:[1,1,0]
	v_pk_fma_f32 v[86:87], v[86:87], s[10:11], v[200:201] op_sel_hi:[1,1,0]
	v_pk_fma_f32 v[88:89], v[88:89], s[10:11], v[200:201] op_sel_hi:[1,1,0]
	v_pk_fma_f32 v[90:91], v[90:91], s[10:11], v[200:201] op_sel_hi:[1,1,0]
	v_exp_f32_e32 v84, v84
	v_exp_f32_e32 v85, v85
	v_exp_f32_e32 v86, v86
	v_exp_f32_e32 v87, v87
	v_pk_fma_f32 v[92:93], v[92:93], s[10:11], v[200:201] op_sel_hi:[1,1,0]
	v_pk_fma_f32 v[94:95], v[94:95], s[10:11], v[200:201] op_sel_hi:[1,1,0]
	v_exp_f32_e32 v88, v88
	v_exp_f32_e32 v89, v89
	v_exp_f32_e32 v90, v90
	v_exp_f32_e32 v91, v91
	v_pk_fma_f32 v[96:97], v[96:97], s[10:11], v[200:201] op_sel_hi:[1,1,0]
	v_pk_fma_f32 v[98:99], v[98:99], s[10:11], v[200:201] op_sel_hi:[1,1,0]
	v_exp_f32_e32 v92, v92
	v_exp_f32_e32 v93, v93
	v_exp_f32_e32 v94, v94
	v_exp_f32_e32 v95, v95
	s_nop 0
	v_exp_f32_e32 v96, v96
	v_exp_f32_e32 v97, v97
	v_exp_f32_e32 v98, v98
	v_exp_f32_e32 v99, v99
	v_pk_add_f32 v[248:249], v[84:85], v[86:87]
	v_pk_add_f32 v[82:83], v[88:89], v[90:91]
	v_pk_add_f32 v[172:173], v[92:93], v[94:95]
	v_pk_add_f32 v[202:203], v[96:97], v[98:99]
	v_cvt_pk_fp8_f32 v84, v84, v85
	v_cvt_pk_fp8_f32 v85, v88, v89
	v_pk_add_f32 v[248:249], v[248:249], v[82:83]
	v_pk_add_f32 v[172:173], v[172:173], v[202:203]
	v_cvt_pk_fp8_f32 v84, v86, v87 op_sel:[0,0,1]
	v_cvt_pk_fp8_f32 v85, v90, v91 op_sel:[0,0,1]
	v_pk_add_f32 v[248:249], v[248:249], v[172:173]
	v_cvt_pk_fp8_f32 v86, v92, v93
	v_cvt_pk_fp8_f32 v87, v96, v97
	v_add_f32_e32 v248, v248, v249
	v_cvt_pk_fp8_f32 v86, v94, v95 op_sel:[0,0,1]
	v_cvt_pk_fp8_f32 v87, v98, v99 op_sel:[0,0,1]
	v_cmp_lt_f32_e32 vcc, 0x43800000, v248
	s_cbranch_vccnz .Lbm3_Ag1_redo
	v_add_f32_e32 v195, v195, v248
	s_waitcnt vmcnt(8)
	v_mfma_f32_16x16x32_fp8_fp8 v[116:119], v[36:37], v[84:85], v[116:119]
	v_mfma_f32_16x16x32_fp8_fp8 v[120:123], v[38:39], v[84:85], v[120:123]
	v_mfma_f32_16x16x32_fp8_fp8 v[124:127], v[40:41], v[84:85], v[124:127]
	v_mfma_f32_16x16x32_fp8_fp8 v[128:131], v[42:43], v[84:85], v[128:131]
	v_mfma_f32_16x16x32_fp8_fp8 v[116:119], v[44:45], v[86:87], v[116:119]
	v_mfma_f32_16x16x32_fp8_fp8 v[120:123], v[46:47], v[86:87], v[120:123]
	v_mfma_f32_16x16x32_fp8_fp8 v[124:127], v[48:49], v[86:87], v[124:127]
	v_mfma_f32_16x16x32_fp8_fp8 v[128:131], v[50:51], v[86:87], v[128:131]
	s_lshr_b32 s29, s48, 8
	s_cmp_eq_u32 s29, 0
	s_cbranch_scc1 .Lbm3_Ag3_skip
	s_branch .Lbm3_Ag1_skip

.Lbm3_Ag1_skip:
	s_bfe_u32 s29, s48, 0x40008
	s_cmp_eq_u32 s29, 0
	s_cbranch_scc1 .Lbm3_Ag2_skip
	s_waitcnt vmcnt(12)
	v_mfma_f32_16x16x32_fp8_fp8 v[84:87], v[2:3], v[182:183], 0
	v_mfma_f32_16x16x32_fp8_fp8 v[88:91], v[6:7], v[182:183], 0
	v_mfma_f32_16x16x32_fp8_fp8 v[92:95], v[12:13], v[182:183], 0
	v_mfma_f32_16x16x32_fp8_fp8 v[96:99], v[16:17], v[182:183], 0
	v_mfma_f32_16x16x32_fp8_fp8 v[84:87], v[4:5], v[184:185], v[84:87]
	v_mfma_f32_16x16x32_fp8_fp8 v[88:91], v[8:9], v[184:185], v[88:91]
	v_mfma_f32_16x16x32_fp8_fp8 v[92:95], v[14:15], v[184:185], v[92:95]
	v_mfma_f32_16x16x32_fp8_fp8 v[96:99], v[18:19], v[184:185], v[96:99]
	v_and_b32_e32 v199, s29, v244
	s_cmp_eq_u32 s50, 1
	v_cmp_ne_u32_e32 vcc, 0, v199
	s_cbranch_scc1 .Lbm3_Ag2_near
	v_add_f32_e32 v200, v81, v192
	v_cndmask_b32_e32 v200, v77, v200, vcc
	s_cmp_eq_u32 s35, 0
	s_cbranch_scc1 .Lbm3_Ag2_first
	v_pk_fma_f32 v[84:85], v[84:85], s[10:11], v[200:201] op_sel_hi:[1,1,0]
	v_pk_fma_f32 v[86:87], v[86:87], s[10:11], v[200:201] op_sel_hi:[1,1,0]
	v_pk_fma_f32 v[88:89], v[88:89], s[10:11], v[200:201] op_sel_hi:[1,1,0]
	v_pk_fma_f32 v[90:91], v[90:91], s[10:11], v[200:201] op_sel_hi:[1,1,0]
	v_exp_f32_e32 v84, v84
	v_exp_f32_e32 v85, v85
	v_exp_f32_e32 v86, v86
	v_exp_f32_e32 v87, v87
	v_pk_fma_f32 v[92:93], v[92:93], s[10:11], v[200:201] op_sel_hi:[1,1,0]
	v_pk_fma_f32 v[94:95], v[94:95], s[10:11], v[200:201] op_sel_hi:[1,1,0]
	v_exp_f32_e32 v88, v88
	v_exp_f32_e32 v89, v89
	v_exp_f32_e32 v90, v90
	v_exp_f32_e32 v91, v91
	v_pk_fma_f32 v[96:97], v[96:97], s[10:11], v[200:201] op_sel_hi:[1,1,0]
	v_pk_fma_f32 v[98:99], v[98:99], s[10:11], v[200:201] op_sel_hi:[1,1,0]
	v_exp_f32_e32 v92, v92
	v_exp_f32_e32 v93, v93
	v_exp_f32_e32 v94, v94
	v_exp_f32_e32 v95, v95
	s_nop 0
	v_exp_f32_e32 v96, v96
	v_exp_f32_e32 v97, v97
	v_exp_f32_e32 v98, v98
	v_exp_f32_e32 v99, v99
	v_pk_add_f32 v[248:249], v[84:85], v[86:87]
	v_pk_add_f32 v[82:83], v[88:89], v[90:91]
	v_pk_add_f32 v[172:173], v[92:93], v[94:95]
	v_pk_add_f32 v[202:203], v[96:97], v[98:99]
	v_cvt_pk_fp8_f32 v84, v84, v85
	v_cvt_pk_fp8_f32 v85, v88, v89
	v_pk_add_f32 v[248:249], v[248:249], v[82:83]
	v_pk_add_f32 v[172:173], v[172:173], v[202:203]
	v_cvt_pk_fp8_f32 v84, v86, v87 op_sel:[0,0,1]
	v_cvt_pk_fp8_f32 v85, v90, v91 op_sel:[0,0,1]
	v_pk_add_f32 v[248:249], v[248:249], v[172:173]
	v_cvt_pk_fp8_f32 v86, v92, v93
	v_cvt_pk_fp8_f32 v87, v96, v97
	v_add_f32_e32 v248, v248, v249
	v_cvt_pk_fp8_f32 v86, v94, v95 op_sel:[0,0,1]
	v_cvt_pk_fp8_f32 v87, v98, v99 op_sel:[0,0,1]
	v_cmp_lt_f32_e32 vcc, 0x43800000, v248
	s_cbranch_vccnz .Lbm3_Ag2_redo
	v_add_f32_e32 v196, v196, v248
	s_waitcnt vmcnt(8)
	v_mfma_f32_16x16x32_fp8_fp8 v[132:135], v[36:37], v[84:85], v[132:135]
	v_mfma_f32_16x16x32_fp8_fp8 v[136:139], v[38:39], v[84:85], v[136:139]
	v_mfma_f32_16x16x32_fp8_fp8 v[140:143], v[40:41], v[84:85], v[140:143]
	v_mfma_f32_16x16x32_fp8_fp8 v[144:147], v[42:43], v[84:85], v[144:147]
	v_mfma_f32_16x16x32_fp8_fp8 v[132:135], v[44:45], v[86:87], v[132:135]
	v_mfma_f32_16x16x32_fp8_fp8 v[136:139], v[46:47], v[86:87], v[136:139]
	v_mfma_f32_16x16x32_fp8_fp8 v[140:143], v[48:49], v[86:87], v[140:143]
	v_mfma_f32_16x16x32_fp8_fp8 v[144:147], v[50:51], v[86:87], v[144:147]
	s_lshr_b32 s29, s48, 12
	s_cmp_eq_u32 s29, 0
	s_cbranch_scc1 .Lbm3_Ag3_skip
	s_branch .Lbm3_Ag2_skip

.Lbm3_blkB:
	s_lshl_b32 s29, s27, 12
	s_add_u32 s30, s40, s29
	s_addc_u32 s31, s41, 0
	global_load_dwordx4 v[2:5], v79, s[30:31]
	global_load_dwordx4 v[6:9], v79, s[30:31] offset:1024
	global_load_dwordx4 v[12:15], v79, s[30:31] offset:2048
	global_load_dwordx4 v[16:19], v79, s[30:31] offset:3072
	s_lshl_b32 s29, s27, 12
	s_add_u32 s30, s62, s29
	s_addc_u32 s31, s63, 0
	global_load_dwordx4 v[36:39], v79, s[30:31]
	global_load_dwordx4 v[40:43], v79, s[30:31] offset:1024
	global_load_dwordx4 v[44:47], v79, s[30:31] offset:2048
	global_load_dwordx4 v[48:51], v79, s[30:31] offset:3072
	s_add_i32 s50, s35, 2
	s_add_i32 s9, s25, -1
	s_min_i32 s50, s50, s9
	s_lshl_b32 s9, s50, 2
	s_add_i32 s9, s9, s46
	v_mov_b32_e32 v76, s9
	ds_read_b32 v76, v76 offset:16384
	s_cmp_ge_i32 s38, s21
	s_cselect_b32 s50, 1, 0
	s_bfe_u32 s29, s48, 0x40000
	s_cmp_eq_u32 s29, 0
	s_cbranch_scc1 .Lbm3_Bg0_skip
	s_waitcnt vmcnt(12)
	v_mfma_f32_16x16x32_fp8_fp8 v[84:87], v[20:21], v[164:165], 0
	v_mfma_f32_16x16x32_fp8_fp8 v[88:91], v[24:25], v[164:165], 0
	v_mfma_f32_16x16x32_fp8_fp8 v[92:95], v[28:29], v[164:165], 0
	v_mfma_f32_16x16x32_fp8_fp8 v[96:99], v[32:33], v[164:165], 0
	v_mfma_f32_16x16x32_fp8_fp8 v[84:87], v[22:23], v[166:167], v[84:87]
	v_mfma_f32_16x16x32_fp8_fp8 v[88:91], v[26:27], v[166:167], v[88:91]
	v_mfma_f32_16x16x32_fp8_fp8 v[92:95], v[30:31], v[166:167], v[92:95]
	v_mfma_f32_16x16x32_fp8_fp8 v[96:99], v[34:35], v[166:167], v[96:99]
	v_and_b32_e32 v199, s29, v244
	s_cmp_eq_u32 s50, 1
	v_cmp_ne_u32_e32 vcc, 0, v199
	s_cbranch_scc1 .Lbm3_Bg0_near
	v_add_f32_e32 v200, v81, v190
	v_cndmask_b32_e32 v200, v77, v200, vcc
	s_cmp_eq_u32 s35, 0
	s_cbranch_scc1 .Lbm3_Bg0_first
	v_pk_fma_f32 v[84:85], v[84:85], s[10:11], v[200:201] op_sel_hi:[1,1,0]
	v_pk_fma_f32 v[86:87], v[86:87], s[10:11], v[200:201] op_sel_hi:[1,1,0]
	v_pk_fma_f32 v[88:89], v[88:89], s[10:11], v[200:201] op_sel_hi:[1,1,0]
	v_pk_fma_f32 v[90:91], v[90:91], s[10:11], v[200:201] op_sel_hi:[1,1,0]
	v_exp_f32_e32 v84, v84
	v_exp_f32_e32 v85, v85
	v_exp_f32_e32 v86, v86
	v_exp_f32_e32 v87, v87
	v_pk_fma_f32 v[92:93], v[92:93], s[10:11], v[200:201] op_sel_hi:[1,1,0]
	v_pk_fma_f32 v[94:95], v[94:95], s[10:11], v[200:201] op_sel_hi:[1,1,0]
	v_exp_f32_e32 v88, v88
	v_exp_f32_e32 v89, v89
	v_exp_f32_e32 v90, v90
	v_exp_f32_e32 v91, v91
	v_pk_fma_f32 v[96:97], v[96:97], s[10:11], v[200:201] op_sel_hi:[1,1,0]
	v_pk_fma_f32 v[98:99], v[98:99], s[10:11], v[200:201] op_sel_hi:[1,1,0]
	v_exp_f32_e32 v92, v92
	v_exp_f32_e32 v93, v93
	v_exp_f32_e32 v94, v94
	v_exp_f32_e32 v95, v95
	s_nop 0
	v_exp_f32_e32 v96, v96
	v_exp_f32_e32 v97, v97
	v_exp_f32_e32 v98, v98
	v_exp_f32_e32 v99, v99
	v_pk_add_f32 v[248:249], v[84:85], v[86:87]
	v_pk_add_f32 v[82:83], v[88:89], v[90:91]
	v_pk_add_f32 v[172:173], v[92:93], v[94:95]
	v_pk_add_f32 v[202:203], v[96:97], v[98:99]
	v_cvt_pk_fp8_f32 v84, v84, v85
	v_cvt_pk_fp8_f32 v85, v88, v89
	v_pk_add_f32 v[248:249], v[248:249], v[82:83]
	v_pk_add_f32 v[172:173], v[172:173], v[202:203]
	v_cvt_pk_fp8_f32 v84, v86, v87 op_sel:[0,0,1]
	v_cvt_pk_fp8_f32 v85, v90, v91 op_sel:[0,0,1]
	v_pk_add_f32 v[248:249], v[248:249], v[172:173]
	v_cvt_pk_fp8_f32 v86, v92, v93
	v_cvt_pk_fp8_f32 v87, v96, v97
	v_add_f32_e32 v248, v248, v249
	v_cvt_pk_fp8_f32 v86, v94, v95 op_sel:[0,0,1]
	v_cvt_pk_fp8_f32 v87, v98, v99 op_sel:[0,0,1]
	v_cmp_lt_f32_e32 vcc, 0x43800000, v248
	s_cbranch_vccnz .Lbm3_Bg0_redo
	v_add_f32_e32 v194, v194, v248
	s_waitcnt vmcnt(8)
	v_mfma_f32_16x16x32_fp8_fp8 v[100:103], v[52:53], v[84:85], v[100:103]
	v_mfma_f32_16x16x32_fp8_fp8 v[104:107], v[54:55], v[84:85], v[104:107]
	v_mfma_f32_16x16x32_fp8_fp8 v[108:111], v[56:57], v[84:85], v[108:111]
	v_mfma_f32_16x16x32_fp8_fp8 v[112:115], v[58:59], v[84:85], v[112:115]
	v_mfma_f32_16x16x32_fp8_fp8 v[100:103], v[60:61], v[86:87], v[100:103]
	v_mfma_f32_16x16x32_fp8_fp8 v[104:107], v[62:63], v[86:87], v[104:107]
	v_mfma_f32_16x16x32_fp8_fp8 v[108:111], v[64:65], v[86:87], v[108:111]
	v_mfma_f32_16x16x32_fp8_fp8 v[112:115], v[66:67], v[86:87], v[112:115]
	s_lshr_b32 s29, s48, 4
	s_cmp_eq_u32 s29, 0
	s_cbranch_scc1 .Lbm3_Bg3_skip
	s_branch .Lbm3_Bg0_skip

.Lbm3_Bg0_skip:
	s_bfe_u32 s29, s48, 0x40004
	s_cmp_eq_u32 s29, 0
	s_cbranch_scc1 .Lbm3_Bg1_skip
	s_waitcnt vmcnt(12)
	v_mfma_f32_16x16x32_fp8_fp8 v[84:87], v[20:21], v[168:169], 0
	v_mfma_f32_16x16x32_fp8_fp8 v[88:91], v[24:25], v[168:169], 0
	v_mfma_f32_16x16x32_fp8_fp8 v[92:95], v[28:29], v[168:169], 0
	v_mfma_f32_16x16x32_fp8_fp8 v[96:99], v[32:33], v[168:169], 0
	v_mfma_f32_16x16x32_fp8_fp8 v[84:87], v[22:23], v[170:171], v[84:87]
	v_mfma_f32_16x16x32_fp8_fp8 v[88:91], v[26:27], v[170:171], v[88:91]
	v_mfma_f32_16x16x32_fp8_fp8 v[92:95], v[30:31], v[170:171], v[92:95]
	v_mfma_f32_16x16x32_fp8_fp8 v[96:99], v[34:35], v[170:171], v[96:99]
	v_and_b32_e32 v199, s29, v244
	s_cmp_eq_u32 s50, 1
	v_cmp_ne_u32_e32 vcc, 0, v199
	s_cbranch_scc1 .Lbm3_Bg1_near
	v_add_f32_e32 v200, v81, v191
	v_cndmask_b32_e32 v200, v77, v200, vcc
	s_cmp_eq_u32 s35, 0
	s_cbranch_scc1 .Lbm3_Bg1_first
	v_pk_fma_f32 v[84:85], v[84:85], s[10:11], v[200:201] op_sel_hi:[1,1,0]
	v_pk_fma_f32 v[86:87], v[86:87], s[10:11], v[200:201] op_sel_hi:[1,1,0]
	v_pk_fma_f32 v[88:89], v[88:89], s[10:11], v[200:201] op_sel_hi:[1,1,0]
	v_pk_fma_f32 v[90:91], v[90:91], s[10:11], v[200:201] op_sel_hi:[1,1,0]
	v_exp_f32_e32 v84, v84
	v_exp_f32_e32 v85, v85
	v_exp_f32_e32 v86, v86
	v_exp_f32_e32 v87, v87
	v_pk_fma_f32 v[92:93], v[92:93], s[10:11], v[200:201] op_sel_hi:[1,1,0]
	v_pk_fma_f32 v[94:95], v[94:95], s[10:11], v[200:201] op_sel_hi:[1,1,0]
	v_exp_f32_e32 v88, v88
	v_exp_f32_e32 v89, v89
	v_exp_f32_e32 v90, v90
	v_exp_f32_e32 v91, v91
	v_pk_fma_f32 v[96:97], v[96:97], s[10:11], v[200:201] op_sel_hi:[1,1,0]
	v_pk_fma_f32 v[98:99], v[98:99], s[10:11], v[200:201] op_sel_hi:[1,1,0]
	v_exp_f32_e32 v92, v92
	v_exp_f32_e32 v93, v93
	v_exp_f32_e32 v94, v94
	v_exp_f32_e32 v95, v95
	s_nop 0
	v_exp_f32_e32 v96, v96
	v_exp_f32_e32 v97, v97
	v_exp_f32_e32 v98, v98
	v_exp_f32_e32 v99, v99
	v_pk_add_f32 v[248:249], v[84:85], v[86:87]
	v_pk_add_f32 v[82:83], v[88:89], v[90:91]
	v_pk_add_f32 v[172:173], v[92:93], v[94:95]
	v_pk_add_f32 v[202:203], v[96:97], v[98:99]
	v_cvt_pk_fp8_f32 v84, v84, v85
	v_cvt_pk_fp8_f32 v85, v88, v89
	v_pk_add_f32 v[248:249], v[248:249], v[82:83]
	v_pk_add_f32 v[172:173], v[172:173], v[202:203]
	v_cvt_pk_fp8_f32 v84, v86, v87 op_sel:[0,0,1]
	v_cvt_pk_fp8_f32 v85, v90, v91 op_sel:[0,0,1]
	v_pk_add_f32 v[248:249], v[248:249], v[172:173]
	v_cvt_pk_fp8_f32 v86, v92, v93
	v_cvt_pk_fp8_f32 v87, v96, v97
	v_add_f32_e32 v248, v248, v249
	v_cvt_pk_fp8_f32 v86, v94, v95 op_sel:[0,0,1]
	v_cvt_pk_fp8_f32 v87, v98, v99 op_sel:[0,0,1]
	v_cmp_lt_f32_e32 vcc, 0x43800000, v248
	s_cbranch_vccnz .Lbm3_Bg1_redo
	v_add_f32_e32 v195, v195, v248
	s_waitcnt vmcnt(8)
	v_mfma_f32_16x16x32_fp8_fp8 v[116:119], v[52:53], v[84:85], v[116:119]
	v_mfma_f32_16x16x32_fp8_fp8 v[120:123], v[54:55], v[84:85], v[120:123]
	v_mfma_f32_16x16x32_fp8_fp8 v[124:127], v[56:57], v[84:85], v[124:127]
	v_mfma_f32_16x16x32_fp8_fp8 v[128:131], v[58:59], v[84:85], v[128:131]
	v_mfma_f32_16x16x32_fp8_fp8 v[116:119], v[60:61], v[86:87], v[116:119]
	v_mfma_f32_16x16x32_fp8_fp8 v[120:123], v[62:63], v[86:87], v[120:123]
	v_mfma_f32_16x16x32_fp8_fp8 v[124:127], v[64:65], v[86:87], v[124:127]
	v_mfma_f32_16x16x32_fp8_fp8 v[128:131], v[66:67], v[86:87], v[128:131]
	s_lshr_b32 s29, s48, 8
	s_cmp_eq_u32 s29, 0
	s_cbranch_scc1 .Lbm3_Bg3_skip
	s_branch .Lbm3_Bg1_skip

.Lbm3_Bg1_skip:
	s_bfe_u32 s29, s48, 0x40008
	s_cmp_eq_u32 s29, 0
	s_cbranch_scc1 .Lbm3_Bg2_skip
	s_waitcnt vmcnt(12)
	v_mfma_f32_16x16x32_fp8_fp8 v[84:87], v[20:21], v[182:183], 0
	v_mfma_f32_16x16x32_fp8_fp8 v[88:91], v[24:25], v[182:183], 0
	v_mfma_f32_16x16x32_fp8_fp8 v[92:95], v[28:29], v[182:183], 0
	v_mfma_f32_16x16x32_fp8_fp8 v[96:99], v[32:33], v[182:183], 0
	v_mfma_f32_16x16x32_fp8_fp8 v[84:87], v[22:23], v[184:185], v[84:87]
	v_mfma_f32_16x16x32_fp8_fp8 v[88:91], v[26:27], v[184:185], v[88:91]
	v_mfma_f32_16x16x32_fp8_fp8 v[92:95], v[30:31], v[184:185], v[92:95]
	v_mfma_f32_16x16x32_fp8_fp8 v[96:99], v[34:35], v[184:185], v[96:99]
	v_and_b32_e32 v199, s29, v244
	s_cmp_eq_u32 s50, 1
	v_cmp_ne_u32_e32 vcc, 0, v199
	s_cbranch_scc1 .Lbm3_Bg2_near
	v_add_f32_e32 v200, v81, v192
	v_cndmask_b32_e32 v200, v77, v200, vcc
	s_cmp_eq_u32 s35, 0
	s_cbranch_scc1 .Lbm3_Bg2_first
	v_pk_fma_f32 v[84:85], v[84:85], s[10:11], v[200:201] op_sel_hi:[1,1,0]
	v_pk_fma_f32 v[86:87], v[86:87], s[10:11], v[200:201] op_sel_hi:[1,1,0]
	v_pk_fma_f32 v[88:89], v[88:89], s[10:11], v[200:201] op_sel_hi:[1,1,0]
	v_pk_fma_f32 v[90:91], v[90:91], s[10:11], v[200:201] op_sel_hi:[1,1,0]
	v_exp_f32_e32 v84, v84
	v_exp_f32_e32 v85, v85
	v_exp_f32_e32 v86, v86
	v_exp_f32_e32 v87, v87
	v_pk_fma_f32 v[92:93], v[92:93], s[10:11], v[200:201] op_sel_hi:[1,1,0]
	v_pk_fma_f32 v[94:95], v[94:95], s[10:11], v[200:201] op_sel_hi:[1,1,0]
	v_exp_f32_e32 v88, v88
	v_exp_f32_e32 v89, v89
	v_exp_f32_e32 v90, v90
	v_exp_f32_e32 v91, v91
	v_pk_fma_f32 v[96:97], v[96:97], s[10:11], v[200:201] op_sel_hi:[1,1,0]
	v_pk_fma_f32 v[98:99], v[98:99], s[10:11], v[200:201] op_sel_hi:[1,1,0]
	v_exp_f32_e32 v92, v92
	v_exp_f32_e32 v93, v93
	v_exp_f32_e32 v94, v94
	v_exp_f32_e32 v95, v95
	s_nop 0
	v_exp_f32_e32 v96, v96
	v_exp_f32_e32 v97, v97
	v_exp_f32_e32 v98, v98
	v_exp_f32_e32 v99, v99
	v_pk_add_f32 v[248:249], v[84:85], v[86:87]
	v_pk_add_f32 v[82:83], v[88:89], v[90:91]
	v_pk_add_f32 v[172:173], v[92:93], v[94:95]
	v_pk_add_f32 v[202:203], v[96:97], v[98:99]
	v_cvt_pk_fp8_f32 v84, v84, v85
	v_cvt_pk_fp8_f32 v85, v88, v89
	v_pk_add_f32 v[248:249], v[248:249], v[82:83]
	v_pk_add_f32 v[172:173], v[172:173], v[202:203]
	v_cvt_pk_fp8_f32 v84, v86, v87 op_sel:[0,0,1]
	v_cvt_pk_fp8_f32 v85, v90, v91 op_sel:[0,0,1]
	v_pk_add_f32 v[248:249], v[248:249], v[172:173]
	v_cvt_pk_fp8_f32 v86, v92, v93
	v_cvt_pk_fp8_f32 v87, v96, v97
	v_add_f32_e32 v248, v248, v249
	v_cvt_pk_fp8_f32 v86, v94, v95 op_sel:[0,0,1]
	v_cvt_pk_fp8_f32 v87, v98, v99 op_sel:[0,0,1]
	v_cmp_lt_f32_e32 vcc, 0x43800000, v248
	s_cbranch_vccnz .Lbm3_Bg2_redo
	v_add_f32_e32 v196, v196, v248
	s_waitcnt vmcnt(8)
	v_mfma_f32_16x16x32_fp8_fp8 v[132:135], v[52:53], v[84:85], v[132:135]
	v_mfma_f32_16x16x32_fp8_fp8 v[136:139], v[54:55], v[84:85], v[136:139]
	v_mfma_f32_16x16x32_fp8_fp8 v[140:143], v[56:57], v[84:85], v[140:143]
	v_mfma_f32_16x16x32_fp8_fp8 v[144:147], v[58:59], v[84:85], v[144:147]
	v_mfma_f32_16x16x32_fp8_fp8 v[132:135], v[60:61], v[86:87], v[132:135]
	v_mfma_f32_16x16x32_fp8_fp8 v[136:139], v[62:63], v[86:87], v[136:139]
	v_mfma_f32_16x16x32_fp8_fp8 v[140:143], v[64:65], v[86:87], v[140:143]
	v_mfma_f32_16x16x32_fp8_fp8 v[144:147], v[66:67], v[86:87], v[144:147]
	s_lshr_b32 s29, s48, 12
	s_cmp_eq_u32 s29, 0
	s_cbranch_scc1 .Lbm3_Bg3_skip
	s_branch .Lbm3_Bg2_skip
